# scan phase: wave 1 prefetches the job's chunk data into L2 ahead of the scanning wave (layer 1 only, LDS progress feedback)
# baseline (speedup 1.0000x reference)
; __device__ __forceinline__ float bf_lo(unsigned u) { return __uint_as_float(u << 16); }
; __device__ __forceinline__ float bf_hi(unsigned u) { return __uint_as_float(u & 0xffff0000u); }
; __device__ __forceinline__ unsigned pk2(float lo, float hi) { return pg8::cvt_pk_bf16(lo, hi); }
; #define SCAN_LOAD_D(slot, cc) { const int c_ = (cc) < NCH ? (cc) : NCH - 1; const bf16_t* bcn = bc0 + (size_t)c_ * 4096; \
;             _Pragma("unroll") for (int t = 0; t < 4; ++t) { cb[slot][t] = *(const u32x2*)(bcn + 256 * t); cm[slot][t] = mixer == 2 ? *(const f32x4*)(mv0 + (size_t)c_ * 64 + 16 * t) : (f32x4){g64, g64, g64, g64}; } }
; __device__ __forceinline__ void scan_phase(const Ctx& X, int wave, int lane) {
;     ...
;         for (int c0 = 0; c0 < NCH; c0 += 4) {
; #pragma unroll
;             for (int k = 0; k < 4; ++k) {
;                 const int c = c0 + k;
;                 SCAN_LOAD_D((k + 3) & 3, c + 3)
;                 bf16_t* bcc = bc0 + (size_t)c * 4096;
; #pragma unroll
;                 for (int t = 0; t < 4; ++t) { u32x2 sp; sp.x = pk2(S[t][0], S[t][1]); sp.y = pk2(S[t][2], S[t][3]);
;                     asm volatile("" : "+v"(sp.x) : "v"(cb[k][t].x));
;                     *(u32x2*)(bcc + 256 * t) = sp;
;                     S[t][0] = cm[k][t].x * S[t][0] + bf_lo(cb[k][t].x); S[t][1] = cm[k][t].y * S[t][1] + bf_hi(cb[k][t].x);
;                     S[t][2] = cm[k][t].z * S[t][2] + bf_lo(cb[k][t].y); S[t][3] = cm[k][t].w * S[t][3] + bf_hi(cb[k][t].y); }
;             }
.Lsd0_loop:
	v_mov_b32_e32 v221, s39
	ds_write_b32 v157, v221
	s_add_i32 s37, s39, 3
	s_min_u32 s37, s37, 0x7f
	s_lshl_b32 s38, s37, 13
	s_add_u32 s82, s44, s38
	s_addc_u32 s83, s45, 0
	global_load_dwordx2 v[48:49], v6, s[82:83]
	global_load_dwordx2 v[50:51], v6, s[82:83] offset:512
	global_load_dwordx2 v[52:53], v6, s[82:83] offset:1024
	global_load_dwordx2 v[54:55], v6, s[82:83] offset:1536
	s_waitcnt vmcnt(24)
	v_cvt_pk_bf16_f32 v120, v8, v9
	v_cvt_pk_bf16_f32 v121, v10, v11
	v_cvt_pk_bf16_f32 v122, v12, v13
	v_cvt_pk_bf16_f32 v123, v14, v15
	v_cvt_pk_bf16_f32 v124, v16, v17
	v_cvt_pk_bf16_f32 v125, v18, v19
	v_cvt_pk_bf16_f32 v126, v20, v21
	v_cvt_pk_bf16_f32 v127, v22, v23
	s_add_i32 s37, s39, 0
	s_lshl_b32 s38, s37, 13
	s_add_u32 s40, s44, s38
	s_addc_u32 s41, s45, 0
	global_store_dwordx2 v6, v[120:121], s[40:41]
	global_store_dwordx2 v6, v[122:123], s[40:41] offset:512
	global_store_dwordx2 v6, v[124:125], s[40:41] offset:1024
	global_store_dwordx2 v6, v[126:127], s[40:41] offset:1536
	v_lshlrev_b32_e32 v128, 16, v24
	v_and_b32_e32 v129, 0xffff0000, v24
	v_lshlrev_b32_e32 v130, 16, v25
	v_and_b32_e32 v131, 0xffff0000, v25
	v_fma_f32 v8, v0, v8, v128
	v_fma_f32 v9, v0, v9, v129
	v_fma_f32 v10, v0, v10, v130
	v_fma_f32 v11, v0, v11, v131
	v_lshlrev_b32_e32 v128, 16, v26
	v_and_b32_e32 v129, 0xffff0000, v26
	v_lshlrev_b32_e32 v130, 16, v27
	v_and_b32_e32 v131, 0xffff0000, v27
	v_fma_f32 v12, v0, v12, v128
	v_fma_f32 v13, v0, v13, v129
	v_fma_f32 v14, v0, v14, v130
	v_fma_f32 v15, v0, v15, v131
	v_lshlrev_b32_e32 v128, 16, v28
	v_and_b32_e32 v129, 0xffff0000, v28
	v_lshlrev_b32_e32 v130, 16, v29
	v_and_b32_e32 v131, 0xffff0000, v29
	v_fma_f32 v16, v0, v16, v128
	v_fma_f32 v17, v0, v17, v129
	v_fma_f32 v18, v0, v18, v130
	v_fma_f32 v19, v0, v19, v131
	v_lshlrev_b32_e32 v128, 16, v30
	v_and_b32_e32 v129, 0xffff0000, v30
	v_lshlrev_b32_e32 v130, 16, v31
	v_and_b32_e32 v131, 0xffff0000, v31
	v_fma_f32 v20, v0, v20, v128
	v_fma_f32 v21, v0, v21, v129
	v_fma_f32 v22, v0, v22, v130
	v_fma_f32 v23, v0, v23, v131
	s_add_i32 s37, s39, 4
	s_min_u32 s37, s37, 0x7f
	s_lshl_b32 s38, s37, 13
	s_add_u32 s82, s44, s38
	s_addc_u32 s83, s45, 0
	global_load_dwordx2 v[24:25], v6, s[82:83]
	global_load_dwordx2 v[26:27], v6, s[82:83] offset:512
	global_load_dwordx2 v[28:29], v6, s[82:83] offset:1024
	global_load_dwordx2 v[30:31], v6, s[82:83] offset:1536
	s_waitcnt vmcnt(24)
	v_cvt_pk_bf16_f32 v120, v8, v9
	v_cvt_pk_bf16_f32 v121, v10, v11
	v_cvt_pk_bf16_f32 v122, v12, v13
	v_cvt_pk_bf16_f32 v123, v14, v15
	v_cvt_pk_bf16_f32 v124, v16, v17
	v_cvt_pk_bf16_f32 v125, v18, v19
	v_cvt_pk_bf16_f32 v126, v20, v21
	v_cvt_pk_bf16_f32 v127, v22, v23
	s_add_i32 s37, s39, 1
	s_lshl_b32 s38, s37, 13
	s_add_u32 s40, s44, s38
	s_addc_u32 s41, s45, 0
	global_store_dwordx2 v6, v[120:121], s[40:41]
	global_store_dwordx2 v6, v[122:123], s[40:41] offset:512
	global_store_dwordx2 v6, v[124:125], s[40:41] offset:1024
	global_store_dwordx2 v6, v[126:127], s[40:41] offset:1536
	v_lshlrev_b32_e32 v128, 16, v32
	v_and_b32_e32 v129, 0xffff0000, v32
	v_lshlrev_b32_e32 v130, 16, v33
	v_and_b32_e32 v131, 0xffff0000, v33
	v_fma_f32 v8, v0, v8, v128
	v_fma_f32 v9, v0, v9, v129
	v_fma_f32 v10, v0, v10, v130
	v_fma_f32 v11, v0, v11, v131
	v_lshlrev_b32_e32 v128, 16, v34
	v_and_b32_e32 v129, 0xffff0000, v34
	v_lshlrev_b32_e32 v130, 16, v35
	v_and_b32_e32 v131, 0xffff0000, v35
	v_fma_f32 v12, v0, v12, v128
	v_fma_f32 v13, v0, v13, v129
	v_fma_f32 v14, v0, v14, v130
	v_fma_f32 v15, v0, v15, v131
	v_lshlrev_b32_e32 v128, 16, v36
	v_and_b32_e32 v129, 0xffff0000, v36
	v_lshlrev_b32_e32 v130, 16, v37
	v_and_b32_e32 v131, 0xffff0000, v37
	v_fma_f32 v16, v0, v16, v128
	v_fma_f32 v17, v0, v17, v129
	v_fma_f32 v18, v0, v18, v130
	v_fma_f32 v19, v0, v19, v131
	v_lshlrev_b32_e32 v128, 16, v38
	v_and_b32_e32 v129, 0xffff0000, v38
	v_lshlrev_b32_e32 v130, 16, v39
	v_and_b32_e32 v131, 0xffff0000, v39
	v_fma_f32 v20, v0, v20, v128
	v_fma_f32 v21, v0, v21, v129
	v_fma_f32 v22, v0, v22, v130
	v_fma_f32 v23, v0, v23, v131
	s_add_i32 s37, s39, 5
	s_min_u32 s37, s37, 0x7f
	s_lshl_b32 s38, s37, 13
	s_add_u32 s82, s44, s38
	s_addc_u32 s83, s45, 0
	global_load_dwordx2 v[32:33], v6, s[82:83]
	global_load_dwordx2 v[34:35], v6, s[82:83] offset:512
	global_load_dwordx2 v[36:37], v6, s[82:83] offset:1024
	global_load_dwordx2 v[38:39], v6, s[82:83] offset:1536
	s_waitcnt vmcnt(24)
; __device__ __forceinline__ float bf_lo(unsigned u) { return __uint_as_float(u << 16); }
; __device__ __forceinline__ float bf_hi(unsigned u) { return __uint_as_float(u & 0xffff0000u); }
; __device__ __forceinline__ unsigned pk2(float lo, float hi) { return pg8::cvt_pk_bf16(lo, hi); }
; #define SCAN_LOAD_D(slot, cc) { const int c_ = (cc) < NCH ? (cc) : NCH - 1; const bf16_t* bcn = bc0 + (size_t)c_ * 4096; \
;             _Pragma("unroll") for (int t = 0; t < 4; ++t) { cb[slot][t] = *(const u32x2*)(bcn + 256 * t); cm[slot][t] = mixer == 2 ? *(const f32x4*)(mv0 + (size_t)c_ * 64 + 16 * t) : (f32x4){g64, g64, g64, g64}; } }
; __device__ __forceinline__ void scan_phase(const Ctx& X, int wave, int lane) {
;     ...
;         for (int c0 = 0; c0 < NCH; c0 += 4) {
; #pragma unroll
;             for (int k = 0; k < 4; ++k) {
;                 const int c = c0 + k;
;                 SCAN_LOAD_D((k + 3) & 3, c + 3)
;                 bf16_t* bcc = bc0 + (size_t)c * 4096;
; #pragma unroll
;                 for (int t = 0; t < 4; ++t) { u32x2 sp; sp.x = pk2(S[t][0], S[t][1]); sp.y = pk2(S[t][2], S[t][3]);
;                     asm volatile("" : "+v"(sp.x) : "v"(cb[k][t].x));
;                     *(u32x2*)(bcc + 256 * t) = sp;
;                     S[t][0] = cm[k][t].x * S[t][0] + bf_lo(cb[k][t].x); S[t][1] = cm[k][t].y * S[t][1] + bf_hi(cb[k][t].x);
;                     S[t][2] = cm[k][t].z * S[t][2] + bf_lo(cb[k][t].y); S[t][3] = cm[k][t].w * S[t][3] + bf_hi(cb[k][t].y); }
;             }
	v_cvt_pk_bf16_f32 v120, v8, v9
	v_cvt_pk_bf16_f32 v121, v10, v11
	v_cvt_pk_bf16_f32 v122, v12, v13
	v_cvt_pk_bf16_f32 v123, v14, v15
	v_cvt_pk_bf16_f32 v124, v16, v17
	v_cvt_pk_bf16_f32 v125, v18, v19
	v_cvt_pk_bf16_f32 v126, v20, v21
	v_cvt_pk_bf16_f32 v127, v22, v23
	s_add_i32 s37, s39, 2
	s_lshl_b32 s38, s37, 13
	s_add_u32 s40, s44, s38
	s_addc_u32 s41, s45, 0
	global_store_dwordx2 v6, v[120:121], s[40:41]
	global_store_dwordx2 v6, v[122:123], s[40:41] offset:512
	global_store_dwordx2 v6, v[124:125], s[40:41] offset:1024
	global_store_dwordx2 v6, v[126:127], s[40:41] offset:1536
	v_lshlrev_b32_e32 v128, 16, v40
	v_and_b32_e32 v129, 0xffff0000, v40
	v_lshlrev_b32_e32 v130, 16, v41
	v_and_b32_e32 v131, 0xffff0000, v41
	v_fma_f32 v8, v0, v8, v128
	v_fma_f32 v9, v0, v9, v129
	v_fma_f32 v10, v0, v10, v130
	v_fma_f32 v11, v0, v11, v131
	v_lshlrev_b32_e32 v128, 16, v42
	v_and_b32_e32 v129, 0xffff0000, v42
	v_lshlrev_b32_e32 v130, 16, v43
	v_and_b32_e32 v131, 0xffff0000, v43
	v_fma_f32 v12, v0, v12, v128
	v_fma_f32 v13, v0, v13, v129
	v_fma_f32 v14, v0, v14, v130
	v_fma_f32 v15, v0, v15, v131
	v_lshlrev_b32_e32 v128, 16, v44
	v_and_b32_e32 v129, 0xffff0000, v44
	v_lshlrev_b32_e32 v130, 16, v45
	v_and_b32_e32 v131, 0xffff0000, v45
	v_fma_f32 v16, v0, v16, v128
	v_fma_f32 v17, v0, v17, v129
	v_fma_f32 v18, v0, v18, v130
	v_fma_f32 v19, v0, v19, v131
	v_lshlrev_b32_e32 v128, 16, v46
	v_and_b32_e32 v129, 0xffff0000, v46
	v_lshlrev_b32_e32 v130, 16, v47
	v_and_b32_e32 v131, 0xffff0000, v47
	v_fma_f32 v20, v0, v20, v128
	v_fma_f32 v21, v0, v21, v129
	v_fma_f32 v22, v0, v22, v130
	v_fma_f32 v23, v0, v23, v131
	s_add_i32 s37, s39, 6
	s_min_u32 s37, s37, 0x7f
	s_lshl_b32 s38, s37, 13
	s_add_u32 s82, s44, s38
	s_addc_u32 s83, s45, 0
	global_load_dwordx2 v[40:41], v6, s[82:83]
	global_load_dwordx2 v[42:43], v6, s[82:83] offset:512
	global_load_dwordx2 v[44:45], v6, s[82:83] offset:1024
	global_load_dwordx2 v[46:47], v6, s[82:83] offset:1536
	s_waitcnt vmcnt(24)
	v_cvt_pk_bf16_f32 v120, v8, v9
	v_cvt_pk_bf16_f32 v121, v10, v11
	v_cvt_pk_bf16_f32 v122, v12, v13
	v_cvt_pk_bf16_f32 v123, v14, v15
	v_cvt_pk_bf16_f32 v124, v16, v17
	v_cvt_pk_bf16_f32 v125, v18, v19
	v_cvt_pk_bf16_f32 v126, v20, v21
	v_cvt_pk_bf16_f32 v127, v22, v23
	s_add_i32 s37, s39, 3
	s_lshl_b32 s38, s37, 13
	s_add_u32 s40, s44, s38
	s_addc_u32 s41, s45, 0
	global_store_dwordx2 v6, v[120:121], s[40:41]
	global_store_dwordx2 v6, v[122:123], s[40:41] offset:512
	global_store_dwordx2 v6, v[124:125], s[40:41] offset:1024
	global_store_dwordx2 v6, v[126:127], s[40:41] offset:1536
	v_lshlrev_b32_e32 v128, 16, v48
	v_and_b32_e32 v129, 0xffff0000, v48
	v_lshlrev_b32_e32 v130, 16, v49
	v_and_b32_e32 v131, 0xffff0000, v49
	v_fma_f32 v8, v0, v8, v128
	v_fma_f32 v9, v0, v9, v129
	v_fma_f32 v10, v0, v10, v130
	v_fma_f32 v11, v0, v11, v131
	v_lshlrev_b32_e32 v128, 16, v50
	v_and_b32_e32 v129, 0xffff0000, v50
	v_lshlrev_b32_e32 v130, 16, v51
	v_and_b32_e32 v131, 0xffff0000, v51
	v_fma_f32 v12, v0, v12, v128
	v_fma_f32 v13, v0, v13, v129
	v_fma_f32 v14, v0, v14, v130
	v_fma_f32 v15, v0, v15, v131
	v_lshlrev_b32_e32 v128, 16, v52
	v_and_b32_e32 v129, 0xffff0000, v52
	v_lshlrev_b32_e32 v130, 16, v53
	v_and_b32_e32 v131, 0xffff0000, v53
	v_fma_f32 v16, v0, v16, v128
	v_fma_f32 v17, v0, v17, v129
	v_fma_f32 v18, v0, v18, v130
	v_fma_f32 v19, v0, v19, v131
	v_lshlrev_b32_e32 v128, 16, v54
	v_and_b32_e32 v129, 0xffff0000, v54
	v_lshlrev_b32_e32 v130, 16, v55
	v_and_b32_e32 v131, 0xffff0000, v55
	v_fma_f32 v20, v0, v20, v128
	v_fma_f32 v21, v0, v21, v129
	v_fma_f32 v22, v0, v22, v130
	v_fma_f32 v23, v0, v23, v131
	s_add_i32 s39, s39, 4
	s_cmpk_lt_u32 s39, 0x80
	s_cbranch_scc1 .Lsd0_loop
	s_branch .LBB0_739

; __device__ __forceinline__ float bf_lo(unsigned u) { return __uint_as_float(u << 16); }
; __device__ __forceinline__ float bf_hi(unsigned u) { return __uint_as_float(u & 0xffff0000u); }
; __device__ __forceinline__ unsigned pk2(float lo, float hi) { return pg8::cvt_pk_bf16(lo, hi); }
; #define SCAN_LOAD_D(slot, cc) { const int c_ = (cc) < NCH ? (cc) : NCH - 1; const bf16_t* bcn = bc0 + (size_t)c_ * 4096; \
;             _Pragma("unroll") for (int t = 0; t < 4; ++t) { cb[slot][t] = *(const u32x2*)(bcn + 256 * t); cm[slot][t] = mixer == 2 ? *(const f32x4*)(mv0 + (size_t)c_ * 64 + 16 * t) : (f32x4){g64, g64, g64, g64}; } }
; __device__ __forceinline__ void scan_phase(const Ctx& X, int wave, int lane) {
;     ...
;         for (int c0 = 0; c0 < NCH; c0 += 4) {
; #pragma unroll
;             for (int k = 0; k < 4; ++k) {
;                 const int c = c0 + k;
;                 SCAN_LOAD_D((k + 3) & 3, c + 3)
;                 bf16_t* bcc = bc0 + (size_t)c * 4096;
; #pragma unroll
;                 for (int t = 0; t < 4; ++t) { u32x2 sp; sp.x = pk2(S[t][0], S[t][1]); sp.y = pk2(S[t][2], S[t][3]);
;                     asm volatile("" : "+v"(sp.x) : "v"(cb[k][t].x));
;                     *(u32x2*)(bcc + 256 * t) = sp;
;                     S[t][0] = cm[k][t].x * S[t][0] + bf_lo(cb[k][t].x); S[t][1] = cm[k][t].y * S[t][1] + bf_hi(cb[k][t].x);
;                     S[t][2] = cm[k][t].z * S[t][2] + bf_lo(cb[k][t].y); S[t][3] = cm[k][t].w * S[t][3] + bf_hi(cb[k][t].y); }
;             }
.Lsd2_loop:
	v_mov_b32_e32 v221, s39
	ds_write_b32 v157, v221
	s_add_i32 s37, s39, 3
	s_min_u32 s37, s37, 0x7f
	s_lshl_b32 s38, s37, 13
	s_add_u32 s82, s44, s38
	s_addc_u32 s83, s45, 0
	global_load_dwordx2 v[48:49], v6, s[82:83]
	global_load_dwordx2 v[50:51], v6, s[82:83] offset:512
	global_load_dwordx2 v[52:53], v6, s[82:83] offset:1024
	global_load_dwordx2 v[54:55], v6, s[82:83] offset:1536
	s_lshl_b32 s38, s37, 8
	s_add_u32 s82, s46, s38
	s_addc_u32 s83, s47, 0
	global_load_dwordx4 v[104:107], v7, s[82:83]
	global_load_dwordx4 v[108:111], v7, s[82:83] offset:64
	global_load_dwordx4 v[112:115], v7, s[82:83] offset:128
	global_load_dwordx4 v[116:119], v7, s[82:83] offset:192
	s_waitcnt vmcnt(36)
	v_cvt_pk_bf16_f32 v120, v8, v9
	v_cvt_pk_bf16_f32 v121, v10, v11
	v_cvt_pk_bf16_f32 v122, v12, v13
	v_cvt_pk_bf16_f32 v123, v14, v15
	v_cvt_pk_bf16_f32 v124, v16, v17
	v_cvt_pk_bf16_f32 v125, v18, v19
	v_cvt_pk_bf16_f32 v126, v20, v21
	v_cvt_pk_bf16_f32 v127, v22, v23
	s_add_i32 s37, s39, 0
	s_lshl_b32 s38, s37, 13
	s_add_u32 s40, s44, s38
	s_addc_u32 s41, s45, 0
	global_store_dwordx2 v6, v[120:121], s[40:41]
	global_store_dwordx2 v6, v[122:123], s[40:41] offset:512
	global_store_dwordx2 v6, v[124:125], s[40:41] offset:1024
	global_store_dwordx2 v6, v[126:127], s[40:41] offset:1536
	v_lshlrev_b32_e32 v128, 16, v24
	v_and_b32_e32 v129, 0xffff0000, v24
	v_lshlrev_b32_e32 v130, 16, v25
	v_and_b32_e32 v131, 0xffff0000, v25
	v_fma_f32 v8, v56, v8, v128
	v_fma_f32 v9, v57, v9, v129
	v_fma_f32 v10, v58, v10, v130
	v_fma_f32 v11, v59, v11, v131
	v_lshlrev_b32_e32 v128, 16, v26
	v_and_b32_e32 v129, 0xffff0000, v26
	v_lshlrev_b32_e32 v130, 16, v27
	v_and_b32_e32 v131, 0xffff0000, v27
	v_fma_f32 v12, v60, v12, v128
	v_fma_f32 v13, v61, v13, v129
	v_fma_f32 v14, v62, v14, v130
	v_fma_f32 v15, v63, v15, v131
	v_lshlrev_b32_e32 v128, 16, v28
	v_and_b32_e32 v129, 0xffff0000, v28
	v_lshlrev_b32_e32 v130, 16, v29
	v_and_b32_e32 v131, 0xffff0000, v29
	v_fma_f32 v16, v64, v16, v128
	v_fma_f32 v17, v65, v17, v129
	v_fma_f32 v18, v66, v18, v130
	v_fma_f32 v19, v67, v19, v131
	v_lshlrev_b32_e32 v128, 16, v30
	v_and_b32_e32 v129, 0xffff0000, v30
	v_lshlrev_b32_e32 v130, 16, v31
	v_and_b32_e32 v131, 0xffff0000, v31
	v_fma_f32 v20, v68, v20, v128
	v_fma_f32 v21, v69, v21, v129
	v_fma_f32 v22, v70, v22, v130
	v_fma_f32 v23, v71, v23, v131
	s_add_i32 s37, s39, 4
	s_min_u32 s37, s37, 0x7f
	s_lshl_b32 s38, s37, 13
	s_add_u32 s82, s44, s38
	s_addc_u32 s83, s45, 0
	global_load_dwordx2 v[24:25], v6, s[82:83]
	global_load_dwordx2 v[26:27], v6, s[82:83] offset:512
	global_load_dwordx2 v[28:29], v6, s[82:83] offset:1024
	global_load_dwordx2 v[30:31], v6, s[82:83] offset:1536
	s_lshl_b32 s38, s37, 8
	s_add_u32 s82, s46, s38
	s_addc_u32 s83, s47, 0
	global_load_dwordx4 v[56:59], v7, s[82:83]
	global_load_dwordx4 v[60:63], v7, s[82:83] offset:64
	global_load_dwordx4 v[64:67], v7, s[82:83] offset:128
	global_load_dwordx4 v[68:71], v7, s[82:83] offset:192
	s_waitcnt vmcnt(36)
	v_cvt_pk_bf16_f32 v120, v8, v9
	v_cvt_pk_bf16_f32 v121, v10, v11
	v_cvt_pk_bf16_f32 v122, v12, v13
	v_cvt_pk_bf16_f32 v123, v14, v15
	v_cvt_pk_bf16_f32 v124, v16, v17
	v_cvt_pk_bf16_f32 v125, v18, v19
	v_cvt_pk_bf16_f32 v126, v20, v21
	v_cvt_pk_bf16_f32 v127, v22, v23
	s_add_i32 s37, s39, 1
	s_lshl_b32 s38, s37, 13
	s_add_u32 s40, s44, s38
	s_addc_u32 s41, s45, 0
	global_store_dwordx2 v6, v[120:121], s[40:41]
	global_store_dwordx2 v6, v[122:123], s[40:41] offset:512
	global_store_dwordx2 v6, v[124:125], s[40:41] offset:1024
	global_store_dwordx2 v6, v[126:127], s[40:41] offset:1536
	v_lshlrev_b32_e32 v128, 16, v32
	v_and_b32_e32 v129, 0xffff0000, v32
	v_lshlrev_b32_e32 v130, 16, v33
	v_and_b32_e32 v131, 0xffff0000, v33
	v_fma_f32 v8, v72, v8, v128
	v_fma_f32 v9, v73, v9, v129
	v_fma_f32 v10, v74, v10, v130
	v_fma_f32 v11, v75, v11, v131
	v_lshlrev_b32_e32 v128, 16, v34
	v_and_b32_e32 v129, 0xffff0000, v34
	v_lshlrev_b32_e32 v130, 16, v35
	v_and_b32_e32 v131, 0xffff0000, v35
	v_fma_f32 v12, v76, v12, v128
	v_fma_f32 v13, v77, v13, v129
	v_fma_f32 v14, v78, v14, v130
	v_fma_f32 v15, v79, v15, v131
	v_lshlrev_b32_e32 v128, 16, v36
	v_and_b32_e32 v129, 0xffff0000, v36
	v_lshlrev_b32_e32 v130, 16, v37
	v_and_b32_e32 v131, 0xffff0000, v37
	v_fma_f32 v16, v80, v16, v128
	v_fma_f32 v17, v81, v17, v129
	v_fma_f32 v18, v82, v18, v130
	v_fma_f32 v19, v83, v19, v131
	v_lshlrev_b32_e32 v128, 16, v38
	v_and_b32_e32 v129, 0xffff0000, v38
	v_lshlrev_b32_e32 v130, 16, v39
	v_and_b32_e32 v131, 0xffff0000, v39
	v_fma_f32 v20, v84, v20, v128
	v_fma_f32 v21, v85, v21, v129
	v_fma_f32 v22, v86, v22, v130
	v_fma_f32 v23, v87, v23, v131
	s_add_i32 s37, s39, 5
	s_min_u32 s37, s37, 0x7f
	s_lshl_b32 s38, s37, 13
	s_add_u32 s82, s44, s38
	s_addc_u32 s83, s45, 0
	global_load_dwordx2 v[32:33], v6, s[82:83]
	global_load_dwordx2 v[34:35], v6, s[82:83] offset:512
	global_load_dwordx2 v[36:37], v6, s[82:83] offset:1024
	global_load_dwordx2 v[38:39], v6, s[82:83] offset:1536
	s_lshl_b32 s38, s37, 8
	s_add_u32 s82, s46, s38
	s_addc_u32 s83, s47, 0
	global_load_dwordx4 v[72:75], v7, s[82:83]
	global_load_dwordx4 v[76:79], v7, s[82:83] offset:64
	global_load_dwordx4 v[80:83], v7, s[82:83] offset:128
	global_load_dwordx4 v[84:87], v7, s[82:83] offset:192
	s_waitcnt vmcnt(36)
; __device__ __forceinline__ float bf_lo(unsigned u) { return __uint_as_float(u << 16); }
; __device__ __forceinline__ float bf_hi(unsigned u) { return __uint_as_float(u & 0xffff0000u); }
; __device__ __forceinline__ unsigned pk2(float lo, float hi) { return pg8::cvt_pk_bf16(lo, hi); }
; #define SCAN_LOAD_D(slot, cc) { const int c_ = (cc) < NCH ? (cc) : NCH - 1; const bf16_t* bcn = bc0 + (size_t)c_ * 4096; \
;             _Pragma("unroll") for (int t = 0; t < 4; ++t) { cb[slot][t] = *(const u32x2*)(bcn + 256 * t); cm[slot][t] = mixer == 2 ? *(const f32x4*)(mv0 + (size_t)c_ * 64 + 16 * t) : (f32x4){g64, g64, g64, g64}; } }
; __device__ __forceinline__ void scan_phase(const Ctx& X, int wave, int lane) {
;     ...
;         for (int c0 = 0; c0 < NCH; c0 += 4) {
; #pragma unroll
;             for (int k = 0; k < 4; ++k) {
;                 const int c = c0 + k;
;                 SCAN_LOAD_D((k + 3) & 3, c + 3)
;                 bf16_t* bcc = bc0 + (size_t)c * 4096;
; #pragma unroll
;                 for (int t = 0; t < 4; ++t) { u32x2 sp; sp.x = pk2(S[t][0], S[t][1]); sp.y = pk2(S[t][2], S[t][3]);
;                     asm volatile("" : "+v"(sp.x) : "v"(cb[k][t].x));
;                     *(u32x2*)(bcc + 256 * t) = sp;
;                     S[t][0] = cm[k][t].x * S[t][0] + bf_lo(cb[k][t].x); S[t][1] = cm[k][t].y * S[t][1] + bf_hi(cb[k][t].x);
;                     S[t][2] = cm[k][t].z * S[t][2] + bf_lo(cb[k][t].y); S[t][3] = cm[k][t].w * S[t][3] + bf_hi(cb[k][t].y); }
;             }
	v_cvt_pk_bf16_f32 v120, v8, v9
	v_cvt_pk_bf16_f32 v121, v10, v11
	v_cvt_pk_bf16_f32 v122, v12, v13
	v_cvt_pk_bf16_f32 v123, v14, v15
	v_cvt_pk_bf16_f32 v124, v16, v17
	v_cvt_pk_bf16_f32 v125, v18, v19
	v_cvt_pk_bf16_f32 v126, v20, v21
	v_cvt_pk_bf16_f32 v127, v22, v23
	s_add_i32 s37, s39, 2
	s_lshl_b32 s38, s37, 13
	s_add_u32 s40, s44, s38
	s_addc_u32 s41, s45, 0
	global_store_dwordx2 v6, v[120:121], s[40:41]
	global_store_dwordx2 v6, v[122:123], s[40:41] offset:512
	global_store_dwordx2 v6, v[124:125], s[40:41] offset:1024
	global_store_dwordx2 v6, v[126:127], s[40:41] offset:1536
	v_lshlrev_b32_e32 v128, 16, v40
	v_and_b32_e32 v129, 0xffff0000, v40
	v_lshlrev_b32_e32 v130, 16, v41
	v_and_b32_e32 v131, 0xffff0000, v41
	v_fma_f32 v8, v88, v8, v128
	v_fma_f32 v9, v89, v9, v129
	v_fma_f32 v10, v90, v10, v130
	v_fma_f32 v11, v91, v11, v131
	v_lshlrev_b32_e32 v128, 16, v42
	v_and_b32_e32 v129, 0xffff0000, v42
	v_lshlrev_b32_e32 v130, 16, v43
	v_and_b32_e32 v131, 0xffff0000, v43
	v_fma_f32 v12, v92, v12, v128
	v_fma_f32 v13, v93, v13, v129
	v_fma_f32 v14, v94, v14, v130
	v_fma_f32 v15, v95, v15, v131
	v_lshlrev_b32_e32 v128, 16, v44
	v_and_b32_e32 v129, 0xffff0000, v44
	v_lshlrev_b32_e32 v130, 16, v45
	v_and_b32_e32 v131, 0xffff0000, v45
	v_fma_f32 v16, v96, v16, v128
	v_fma_f32 v17, v97, v17, v129
	v_fma_f32 v18, v98, v18, v130
	v_fma_f32 v19, v99, v19, v131
	v_lshlrev_b32_e32 v128, 16, v46
	v_and_b32_e32 v129, 0xffff0000, v46
	v_lshlrev_b32_e32 v130, 16, v47
	v_and_b32_e32 v131, 0xffff0000, v47
	v_fma_f32 v20, v100, v20, v128
	v_fma_f32 v21, v101, v21, v129
	v_fma_f32 v22, v102, v22, v130
	v_fma_f32 v23, v103, v23, v131
	s_add_i32 s37, s39, 6
	s_min_u32 s37, s37, 0x7f
	s_lshl_b32 s38, s37, 13
	s_add_u32 s82, s44, s38
	s_addc_u32 s83, s45, 0
	global_load_dwordx2 v[40:41], v6, s[82:83]
	global_load_dwordx2 v[42:43], v6, s[82:83] offset:512
	global_load_dwordx2 v[44:45], v6, s[82:83] offset:1024
	global_load_dwordx2 v[46:47], v6, s[82:83] offset:1536
	s_lshl_b32 s38, s37, 8
	s_add_u32 s82, s46, s38
	s_addc_u32 s83, s47, 0
	global_load_dwordx4 v[88:91], v7, s[82:83]
	global_load_dwordx4 v[92:95], v7, s[82:83] offset:64
	global_load_dwordx4 v[96:99], v7, s[82:83] offset:128
	global_load_dwordx4 v[100:103], v7, s[82:83] offset:192
	s_waitcnt vmcnt(36)
	v_cvt_pk_bf16_f32 v120, v8, v9
	v_cvt_pk_bf16_f32 v121, v10, v11
	v_cvt_pk_bf16_f32 v122, v12, v13
	v_cvt_pk_bf16_f32 v123, v14, v15
	v_cvt_pk_bf16_f32 v124, v16, v17
	v_cvt_pk_bf16_f32 v125, v18, v19
	v_cvt_pk_bf16_f32 v126, v20, v21
	v_cvt_pk_bf16_f32 v127, v22, v23
	s_add_i32 s37, s39, 3
	s_lshl_b32 s38, s37, 13
	s_add_u32 s40, s44, s38
	s_addc_u32 s41, s45, 0
	global_store_dwordx2 v6, v[120:121], s[40:41]
	global_store_dwordx2 v6, v[122:123], s[40:41] offset:512
	global_store_dwordx2 v6, v[124:125], s[40:41] offset:1024
	global_store_dwordx2 v6, v[126:127], s[40:41] offset:1536
	v_lshlrev_b32_e32 v128, 16, v48
	v_and_b32_e32 v129, 0xffff0000, v48
	v_lshlrev_b32_e32 v130, 16, v49
	v_and_b32_e32 v131, 0xffff0000, v49
	v_fma_f32 v8, v104, v8, v128
	v_fma_f32 v9, v105, v9, v129
	v_fma_f32 v10, v106, v10, v130
	v_fma_f32 v11, v107, v11, v131
	v_lshlrev_b32_e32 v128, 16, v50
	v_and_b32_e32 v129, 0xffff0000, v50
	v_lshlrev_b32_e32 v130, 16, v51
	v_and_b32_e32 v131, 0xffff0000, v51
	v_fma_f32 v12, v108, v12, v128
	v_fma_f32 v13, v109, v13, v129
	v_fma_f32 v14, v110, v14, v130
	v_fma_f32 v15, v111, v15, v131
	v_lshlrev_b32_e32 v128, 16, v52
	v_and_b32_e32 v129, 0xffff0000, v52
	v_lshlrev_b32_e32 v130, 16, v53
	v_and_b32_e32 v131, 0xffff0000, v53
	v_fma_f32 v16, v112, v16, v128
	v_fma_f32 v17, v113, v17, v129
	v_fma_f32 v18, v114, v18, v130
	v_fma_f32 v19, v115, v19, v131
	v_lshlrev_b32_e32 v128, 16, v54
	v_and_b32_e32 v129, 0xffff0000, v54
	v_lshlrev_b32_e32 v130, 16, v55
	v_and_b32_e32 v131, 0xffff0000, v55
	v_fma_f32 v20, v116, v20, v128
	v_fma_f32 v21, v117, v21, v129
	v_fma_f32 v22, v118, v22, v130
	v_fma_f32 v23, v119, v23, v131
	s_add_i32 s39, s39, 4
	s_cmpk_lt_u32 s39, 0x80
	s_cbranch_scc1 .Lsd2_loop
	s_branch .LBB0_739

; __device__ __forceinline__ float bf_lo(unsigned u) { return __uint_as_float(u << 16); }
; __device__ __forceinline__ float bf_hi(unsigned u) { return __uint_as_float(u & 0xffff0000u); }
; __device__ __forceinline__ unsigned pk2(float lo, float hi) { return pg8::cvt_pk_bf16(lo, hi); }
; __device__ __forceinline__ void scan_phase(const Ctx& X, int wave, int lane) {
;     ...
;         for (int c0 = 0; c0 < NCH; c0 += 4) {
; #pragma unroll
;             for (int k = 0; k < 4; ++k) {
;                 const int c = c0 + k;
;                 SCAN_LOAD_G((k + 3) & 3, c + 3)
;                 bf16_t* bcc = bc0 + (size_t)c * 4096;
;                 u32x2 sp[4];
; #pragma unroll
;                 for (int t = 0; t < 4; ++t) { sp[t].x = pk2(S[t][0], S[t][1]); sp[t].y = pk2(S[t][2], S[t][3]);
;                     asm volatile("" : "+v"(sp[t].x) : "v"(cb[k][t].x));
;                     *(u32x2*)(bcc + 256 * t) = sp[t]; }
;                 bf16x8 bfr[2];
; #pragma unroll
;                 for (int s2 = 0; s2 < 2; ++s2) { u32x4 w; w.x = sp[2 * s2].x; w.y = sp[2 * s2].y; w.z = sp[2 * s2 + 1].x; w.w = sp[2 * s2 + 1].y; bfr[s2] = __builtin_bit_cast(bf16x8, w); }
; #pragma unroll
;                 for (int t = 0; t < 4; ++t) {
;                     f32x4 acc = (f32x4){bf_lo(cb[k][t].x), bf_hi(cb[k][t].x), bf_lo(cb[k][t].y), bf_hi(cb[k][t].y)};
; #pragma unroll
;                     for (int s2 = 0; s2 < 2; ++s2) { u32x4 w; w.x = ca[k][t][s2][0].x; w.y = ca[k][t][s2][0].y; w.z = ca[k][t][s2][1].x; w.w = ca[k][t][s2][1].y;
;                         acc = __builtin_amdgcn_mfma_f32_16x16x32_bf16(__builtin_bit_cast(bf16x8, w), bfr[s2], acc, 0, 0, 0); }
;                     S[t][0] = acc[0]; S[t][1] = acc[1]; S[t][2] = acc[2]; S[t][3] = acc[3];
;                 }
;             }
.Lsg_loop:
	v_mov_b32_e32 v221, s39
	ds_write_b32 v157, v221
	s_add_i32 s37, s39, 3
	s_min_u32 s37, s37, 0x7f
	s_lshl_b32 s38, s37, 13
	s_add_u32 s82, s44, s38
	s_addc_u32 s83, s45, 0
	global_load_dwordx2 v[48:49], v6, s[82:83]
	global_load_dwordx2 v[50:51], v6, s[82:83] offset:512
	global_load_dwordx2 v[52:53], v6, s[82:83] offset:1024
	global_load_dwordx2 v[54:55], v6, s[82:83] offset:1536
	s_add_u32 s82, s46, s38
	s_addc_u32 s83, s47, 0
	global_load_dwordx4 v[176:179], v7, s[82:83]
	global_load_dwordx4 v[184:187], v7, s[82:83] offset:1024
	global_load_dwordx4 v[188:191], v7, s[82:83] offset:2048
	global_load_dwordx4 v[192:195], v7, s[82:83] offset:3072
	global_load_dwordx4 v[196:199], v129, s[82:83]
	global_load_dwordx4 v[200:203], v129, s[82:83] offset:1024
	global_load_dwordx4 v[204:207], v129, s[82:83] offset:2048
	global_load_dwordx4 v[208:211], v129, s[82:83] offset:3072
	s_waitcnt vmcnt(48)
	v_cvt_pk_bf16_f32 v120, v8, v9
	v_cvt_pk_bf16_f32 v121, v10, v11
	v_cvt_pk_bf16_f32 v122, v12, v13
	v_cvt_pk_bf16_f32 v123, v14, v15
	v_cvt_pk_bf16_f32 v124, v16, v17
	v_cvt_pk_bf16_f32 v125, v18, v19
	v_cvt_pk_bf16_f32 v126, v20, v21
	v_cvt_pk_bf16_f32 v127, v22, v23
	s_add_i32 s37, s39, 0
	s_lshl_b32 s38, s37, 13
	s_add_u32 s40, s44, s38
	s_addc_u32 s41, s45, 0
	global_store_dwordx2 v6, v[120:121], s[40:41]
	global_store_dwordx2 v6, v[122:123], s[40:41] offset:512
	global_store_dwordx2 v6, v[124:125], s[40:41] offset:1024
	global_store_dwordx2 v6, v[126:127], s[40:41] offset:1536
	v_lshlrev_b32_e32 v8, 16, v24
	v_and_b32_e32 v9, 0xffff0000, v24
	v_lshlrev_b32_e32 v10, 16, v25
	v_and_b32_e32 v11, 0xffff0000, v25
	v_lshlrev_b32_e32 v12, 16, v26
	v_and_b32_e32 v13, 0xffff0000, v26
	v_lshlrev_b32_e32 v14, 16, v27
	v_and_b32_e32 v15, 0xffff0000, v27
	v_lshlrev_b32_e32 v16, 16, v28
	v_and_b32_e32 v17, 0xffff0000, v28
	v_lshlrev_b32_e32 v18, 16, v29
	v_and_b32_e32 v19, 0xffff0000, v29
	v_lshlrev_b32_e32 v20, 16, v30
	v_and_b32_e32 v21, 0xffff0000, v30
	v_lshlrev_b32_e32 v22, 16, v31
	v_and_b32_e32 v23, 0xffff0000, v31
	s_nop 1
	v_mfma_f32_16x16x32_bf16 v[8:11], v[56:59], v[120:123], v[8:11]
	v_mfma_f32_16x16x32_bf16 v[12:15], v[64:67], v[120:123], v[12:15]
	v_mfma_f32_16x16x32_bf16 v[16:19], v[72:75], v[120:123], v[16:19]
	v_mfma_f32_16x16x32_bf16 v[20:23], v[80:83], v[120:123], v[20:23]
	v_mfma_f32_16x16x32_bf16 v[8:11], v[60:63], v[124:127], v[8:11]
	v_mfma_f32_16x16x32_bf16 v[12:15], v[68:71], v[124:127], v[12:15]
	v_mfma_f32_16x16x32_bf16 v[16:19], v[76:79], v[124:127], v[16:19]
	v_mfma_f32_16x16x32_bf16 v[20:23], v[84:87], v[124:127], v[20:23]
	s_add_i32 s37, s39, 4
	s_min_u32 s37, s37, 0x7f
	s_lshl_b32 s38, s37, 13
	s_add_u32 s82, s44, s38
	s_addc_u32 s83, s45, 0
	global_load_dwordx2 v[24:25], v6, s[82:83]
	global_load_dwordx2 v[26:27], v6, s[82:83] offset:512
	global_load_dwordx2 v[28:29], v6, s[82:83] offset:1024
	global_load_dwordx2 v[30:31], v6, s[82:83] offset:1536
	s_add_u32 s82, s46, s38
	s_addc_u32 s83, s47, 0
	global_load_dwordx4 v[56:59], v7, s[82:83]
	global_load_dwordx4 v[60:63], v7, s[82:83] offset:1024
	global_load_dwordx4 v[64:67], v7, s[82:83] offset:2048
	global_load_dwordx4 v[68:71], v7, s[82:83] offset:3072
	global_load_dwordx4 v[72:75], v129, s[82:83]
	global_load_dwordx4 v[76:79], v129, s[82:83] offset:1024
	global_load_dwordx4 v[80:83], v129, s[82:83] offset:2048
	global_load_dwordx4 v[84:87], v129, s[82:83] offset:3072
	s_waitcnt vmcnt(48)
	v_cvt_pk_bf16_f32 v120, v8, v9
	v_cvt_pk_bf16_f32 v121, v10, v11
	v_cvt_pk_bf16_f32 v122, v12, v13
	v_cvt_pk_bf16_f32 v123, v14, v15
	v_cvt_pk_bf16_f32 v124, v16, v17
	v_cvt_pk_bf16_f32 v125, v18, v19
	v_cvt_pk_bf16_f32 v126, v20, v21
	v_cvt_pk_bf16_f32 v127, v22, v23
	s_add_i32 s37, s39, 1
	s_lshl_b32 s38, s37, 13
	s_add_u32 s40, s44, s38
	s_addc_u32 s41, s45, 0
	global_store_dwordx2 v6, v[120:121], s[40:41]
	global_store_dwordx2 v6, v[122:123], s[40:41] offset:512
	global_store_dwordx2 v6, v[124:125], s[40:41] offset:1024
	global_store_dwordx2 v6, v[126:127], s[40:41] offset:1536
	v_lshlrev_b32_e32 v8, 16, v32
	v_and_b32_e32 v9, 0xffff0000, v32
	v_lshlrev_b32_e32 v10, 16, v33
	v_and_b32_e32 v11, 0xffff0000, v33
	v_lshlrev_b32_e32 v12, 16, v34
	v_and_b32_e32 v13, 0xffff0000, v34
	v_lshlrev_b32_e32 v14, 16, v35
	v_and_b32_e32 v15, 0xffff0000, v35
	v_lshlrev_b32_e32 v16, 16, v36
	v_and_b32_e32 v17, 0xffff0000, v36
	v_lshlrev_b32_e32 v18, 16, v37
	v_and_b32_e32 v19, 0xffff0000, v37
	v_lshlrev_b32_e32 v20, 16, v38
	v_and_b32_e32 v21, 0xffff0000, v38
	v_lshlrev_b32_e32 v22, 16, v39
	v_and_b32_e32 v23, 0xffff0000, v39
	s_nop 1
	v_mfma_f32_16x16x32_bf16 v[8:11], v[88:91], v[120:123], v[8:11]
	v_mfma_f32_16x16x32_bf16 v[12:15], v[96:99], v[120:123], v[12:15]
	v_mfma_f32_16x16x32_bf16 v[16:19], v[104:107], v[120:123], v[16:19]
	v_mfma_f32_16x16x32_bf16 v[20:23], v[112:115], v[120:123], v[20:23]
	v_mfma_f32_16x16x32_bf16 v[8:11], v[92:95], v[124:127], v[8:11]
	v_mfma_f32_16x16x32_bf16 v[12:15], v[100:103], v[124:127], v[12:15]
	v_mfma_f32_16x16x32_bf16 v[16:19], v[108:111], v[124:127], v[16:19]
	v_mfma_f32_16x16x32_bf16 v[20:23], v[116:119], v[124:127], v[20:23]
	s_add_i32 s37, s39, 5
	s_min_u32 s37, s37, 0x7f
	s_lshl_b32 s38, s37, 13
	s_add_u32 s82, s44, s38
	s_addc_u32 s83, s45, 0
	global_load_dwordx2 v[32:33], v6, s[82:83]
	global_load_dwordx2 v[34:35], v6, s[82:83] offset:512
	global_load_dwordx2 v[36:37], v6, s[82:83] offset:1024
	global_load_dwordx2 v[38:39], v6, s[82:83] offset:1536
	s_add_u32 s82, s46, s38
	s_addc_u32 s83, s47, 0
	global_load_dwordx4 v[88:91], v7, s[82:83]
	global_load_dwordx4 v[92:95], v7, s[82:83] offset:1024
	global_load_dwordx4 v[96:99], v7, s[82:83] offset:2048
	global_load_dwordx4 v[100:103], v7, s[82:83] offset:3072
	global_load_dwordx4 v[104:107], v129, s[82:83]
	global_load_dwordx4 v[108:111], v129, s[82:83] offset:1024
	global_load_dwordx4 v[112:115], v129, s[82:83] offset:2048
	global_load_dwordx4 v[116:119], v129, s[82:83] offset:3072
	s_waitcnt vmcnt(48)
; __device__ __forceinline__ float bf_lo(unsigned u) { return __uint_as_float(u << 16); }
; __device__ __forceinline__ float bf_hi(unsigned u) { return __uint_as_float(u & 0xffff0000u); }
; __device__ __forceinline__ void scan_phase(const Ctx& X, int wave, int lane) {
;     const int job = blockIdx.x;
;     if (job >= 192 || wave != 0) return;
;     asm volatile("" : "+v"(lane));
;     const int mixer = job >> 6, rem = job & 63, bh = rem >> 2, vg = rem & 3;
;     const int uid0 = (mixer * 16 + bh) * NCH;
;     const int r = lane & 15, q = lane >> 4;
;     bf16_t* bc0 = WSP(bf16_t, WS_BCS) + (size_t)uid0 * 4096 + (vg * 4 * 64 + lane) * 4;
;     ...
; #pragma unroll
;                 for (int t = 0; t < 4; ++t) {
;                     f32x4 acc = (f32x4){bf_lo(cb[k][t].x), bf_hi(cb[k][t].x), bf_lo(cb[k][t].y), bf_hi(cb[k][t].y)};
; #pragma unroll
;                     for (int s2 = 0; s2 < 2; ++s2) { u32x4 w; w.x = ca[k][t][s2][0].x; w.y = ca[k][t][s2][0].y; w.z = ca[k][t][s2][1].x; w.w = ca[k][t][s2][1].y;
;                         acc = __builtin_amdgcn_mfma_f32_16x16x32_bf16(__builtin_bit_cast(bf16x8, w), bfr[s2], acc, 0, 0, 0); }
;                     S[t][0] = acc[0]; S[t][1] = acc[1]; S[t][2] = acc[2]; S[t][3] = acc[3];
;                 }
;             }
;         }
	v_cvt_pk_bf16_f32 v120, v8, v9
	v_cvt_pk_bf16_f32 v121, v10, v11
	v_cvt_pk_bf16_f32 v122, v12, v13
	v_cvt_pk_bf16_f32 v123, v14, v15
	v_cvt_pk_bf16_f32 v124, v16, v17
	v_cvt_pk_bf16_f32 v125, v18, v19
	v_cvt_pk_bf16_f32 v126, v20, v21
	v_cvt_pk_bf16_f32 v127, v22, v23
	s_add_i32 s37, s39, 2
	s_lshl_b32 s38, s37, 13
	s_add_u32 s40, s44, s38
	s_addc_u32 s41, s45, 0
	global_store_dwordx2 v6, v[120:121], s[40:41]
	global_store_dwordx2 v6, v[122:123], s[40:41] offset:512
	global_store_dwordx2 v6, v[124:125], s[40:41] offset:1024
	global_store_dwordx2 v6, v[126:127], s[40:41] offset:1536
	v_lshlrev_b32_e32 v8, 16, v40
	v_and_b32_e32 v9, 0xffff0000, v40
	v_lshlrev_b32_e32 v10, 16, v41
	v_and_b32_e32 v11, 0xffff0000, v41
	v_lshlrev_b32_e32 v12, 16, v42
	v_and_b32_e32 v13, 0xffff0000, v42
	v_lshlrev_b32_e32 v14, 16, v43
	v_and_b32_e32 v15, 0xffff0000, v43
	v_lshlrev_b32_e32 v16, 16, v44
	v_and_b32_e32 v17, 0xffff0000, v44
	v_lshlrev_b32_e32 v18, 16, v45
	v_and_b32_e32 v19, 0xffff0000, v45
	v_lshlrev_b32_e32 v20, 16, v46
	v_and_b32_e32 v21, 0xffff0000, v46
	v_lshlrev_b32_e32 v22, 16, v47
	v_and_b32_e32 v23, 0xffff0000, v47
	s_nop 1
	v_mfma_f32_16x16x32_bf16 v[8:11], v[132:135], v[120:123], v[8:11]
	v_mfma_f32_16x16x32_bf16 v[12:15], v[140:143], v[120:123], v[12:15]
	v_mfma_f32_16x16x32_bf16 v[16:19], v[148:151], v[120:123], v[16:19]
	v_mfma_f32_16x16x32_bf16 v[20:23], v[168:171], v[120:123], v[20:23]
	v_mfma_f32_16x16x32_bf16 v[8:11], v[136:139], v[124:127], v[8:11]
	v_mfma_f32_16x16x32_bf16 v[12:15], v[144:147], v[124:127], v[12:15]
	v_mfma_f32_16x16x32_bf16 v[16:19], v[164:167], v[124:127], v[16:19]
	v_mfma_f32_16x16x32_bf16 v[20:23], v[172:175], v[124:127], v[20:23]
	s_add_i32 s37, s39, 6
	s_min_u32 s37, s37, 0x7f
	s_lshl_b32 s38, s37, 13
	s_add_u32 s82, s44, s38
	s_addc_u32 s83, s45, 0
	global_load_dwordx2 v[40:41], v6, s[82:83]
	global_load_dwordx2 v[42:43], v6, s[82:83] offset:512
	global_load_dwordx2 v[44:45], v6, s[82:83] offset:1024
	global_load_dwordx2 v[46:47], v6, s[82:83] offset:1536
	s_add_u32 s82, s46, s38
	s_addc_u32 s83, s47, 0
	global_load_dwordx4 v[132:135], v7, s[82:83]
	global_load_dwordx4 v[136:139], v7, s[82:83] offset:1024
	global_load_dwordx4 v[140:143], v7, s[82:83] offset:2048
	global_load_dwordx4 v[144:147], v7, s[82:83] offset:3072
	global_load_dwordx4 v[148:151], v129, s[82:83]
	global_load_dwordx4 v[164:167], v129, s[82:83] offset:1024
	global_load_dwordx4 v[168:171], v129, s[82:83] offset:2048
	global_load_dwordx4 v[172:175], v129, s[82:83] offset:3072
	s_waitcnt vmcnt(48)
	v_cvt_pk_bf16_f32 v120, v8, v9
	v_cvt_pk_bf16_f32 v121, v10, v11
	v_cvt_pk_bf16_f32 v122, v12, v13
	v_cvt_pk_bf16_f32 v123, v14, v15
	v_cvt_pk_bf16_f32 v124, v16, v17
	v_cvt_pk_bf16_f32 v125, v18, v19
	v_cvt_pk_bf16_f32 v126, v20, v21
	v_cvt_pk_bf16_f32 v127, v22, v23
	s_add_i32 s37, s39, 3
	s_lshl_b32 s38, s37, 13
	s_add_u32 s40, s44, s38
	s_addc_u32 s41, s45, 0
	global_store_dwordx2 v6, v[120:121], s[40:41]
	global_store_dwordx2 v6, v[122:123], s[40:41] offset:512
	global_store_dwordx2 v6, v[124:125], s[40:41] offset:1024
	global_store_dwordx2 v6, v[126:127], s[40:41] offset:1536
	v_lshlrev_b32_e32 v8, 16, v48
	v_and_b32_e32 v9, 0xffff0000, v48
	v_lshlrev_b32_e32 v10, 16, v49
	v_and_b32_e32 v11, 0xffff0000, v49
	v_lshlrev_b32_e32 v12, 16, v50
	v_and_b32_e32 v13, 0xffff0000, v50
	v_lshlrev_b32_e32 v14, 16, v51
	v_and_b32_e32 v15, 0xffff0000, v51
	v_lshlrev_b32_e32 v16, 16, v52
	v_and_b32_e32 v17, 0xffff0000, v52
	v_lshlrev_b32_e32 v18, 16, v53
	v_and_b32_e32 v19, 0xffff0000, v53
	v_lshlrev_b32_e32 v20, 16, v54
	v_and_b32_e32 v21, 0xffff0000, v54
	v_lshlrev_b32_e32 v22, 16, v55
	v_and_b32_e32 v23, 0xffff0000, v55
	s_nop 1
	v_mfma_f32_16x16x32_bf16 v[8:11], v[176:179], v[120:123], v[8:11]
	v_mfma_f32_16x16x32_bf16 v[12:15], v[188:191], v[120:123], v[12:15]
	v_mfma_f32_16x16x32_bf16 v[16:19], v[196:199], v[120:123], v[16:19]
	v_mfma_f32_16x16x32_bf16 v[20:23], v[204:207], v[120:123], v[20:23]
	v_mfma_f32_16x16x32_bf16 v[8:11], v[184:187], v[124:127], v[8:11]
	v_mfma_f32_16x16x32_bf16 v[12:15], v[192:195], v[124:127], v[12:15]
	v_mfma_f32_16x16x32_bf16 v[16:19], v[200:203], v[124:127], v[16:19]
	v_mfma_f32_16x16x32_bf16 v[20:23], v[208:211], v[124:127], v[20:23]
	s_add_i32 s39, s39, 4
	s_cmpk_lt_u32 s39, 0x80
	s_cbranch_scc1 .Lsg_loop
	s_branch .LBB0_739
.LBB0_739:
	v_readfirstlane_b32 s98, v224
	s_lshr_b32 s98, s98, 6
	s_cmp_lg_u32 s98, 1
	s_cbranch_scc1 .Lscanpf_done
	s_cmpk_ge_u32 s2, 0xc0
	s_cbranch_scc1 .Lscanpf_done
	s_and_b64 vcc, exec, s[26:27]
	s_cbranch_vccnz .Lscanpf_done
	ds_write_b32 v157, v157
	s_lshr_b32 s99, s2, 6
	s_and_b32 s20, s2, 63
	s_lshr_b32 s21, s20, 2
	s_and_b32 s20, s20, 3
	s_lshl_b32 s25, s99, 4
	s_add_i32 s25, s25, s21
	s_lshl_b32 s25, s25, 20
	s_lshl_b32 s20, s20, 11
	s_add_u32 s44, s30, 0x3500000
	s_addc_u32 s45, s31, 0
	s_add_u32 s44, s44, s25
	s_addc_u32 s45, s45, 0
	s_add_u32 s44, s44, s20
	s_addc_u32 s45, s45, 0
	s_add_u32 s46, s30, 0x5500000
	s_addc_u32 s47, s31, 0
	s_add_u32 s46, s46, s25
	s_addc_u32 s47, s47, 0
	s_cmp_eq_u32 s99, 2
	s_cbranch_scc0 .Lscanpf_setup
	s_lshl_b32 s21, s21, 15
	s_add_u32 s46, s30, 0x1f600000
	s_addc_u32 s47, s31, 0
	s_add_u32 s46, s46, s21
	s_addc_u32 s47, s47, 0
.Lscanpf_setup:
	v_lshlrev_b32_e32 v246, 7, v232
	v_add_u32_e32 v247, 0x2000, v246
	v_add_u32_e32 v248, 0x4000, v246
	v_add_u32_e32 v249, 0x6000, v246
	v_and_b32_e32 v250, 15, v232
	v_lshrrev_b32_e32 v251, 4, v232
	v_lshlrev_b32_e32 v250, 7, v250
	v_lshl_add_u32 v250, v251, 13, v250
	v_and_b32_e32 v251, 7, v232
	v_lshlrev_b32_e32 v251, 7, v251
	s_mov_b32 s37, 0
	s_mov_b32 s38, 0
.Lscanpf_loop:
	ds_read_b32 v220, v157
	s_waitcnt lgkmcnt(0)
	v_readfirstlane_b32 s39, v220
	s_min_u32 s39, s39, 0x80
	s_add_i32 s39, s39, 24
	s_lshl_b32 s40, s37, 2
	s_cmp_gt_u32 s40, s39
	s_cbranch_scc0 .Lscanpf_issue
	s_sleep 2
	s_add_i32 s38, s38, 1
	s_cmp_lt_u32 s38, 0x20000
	s_cbranch_scc1 .Lscanpf_loop
	s_branch .Lscanpf_done
.Lscanpf_issue:
	s_lshl_b32 s40, s37, 15
	s_add_u32 s82, s44, s40
	s_addc_u32 s83, s45, 0
	global_load_dword v234, v250, s[82:83]
	s_cmp_eq_u32 s99, 1
	s_cbranch_scc0 .Lscanpf_nomm
	s_add_u32 s82, s46, s40
	s_addc_u32 s83, s47, 0
	global_load_dword v234, v246, s[82:83]
	global_load_dword v234, v247, s[82:83]
	global_load_dword v234, v248, s[82:83]
	global_load_dword v234, v249, s[82:83]
.Lscanpf_nomm:
	s_cmp_eq_u32 s99, 2
	s_cbranch_scc0 .Lscanpf_next
	s_lshl_b32 s40, s37, 10
	s_add_u32 s82, s46, s40
	s_addc_u32 s83, s47, 0
	global_load_dword v234, v251, s[82:83]
.Lscanpf_next:
	s_add_i32 s37, s37, 1
	s_cmp_lt_u32 s37, 32
	s_cbranch_scc1 .Lscanpf_loop

; __device__ __forceinline__ unsigned xb_ld(unsigned* p)              { return __hip_atomic_load(p, __ATOMIC_RELAXED, __HIP_MEMORY_SCOPE_AGENT); }
; #define XB_SPIN(cond, bar) do { unsigned _sp = 0; while (cond) { __builtin_amdgcn_s_sleep(1); \
;     if ((++_sp & 255u) == 0u) { if (xb_ld(&(bar)[XB_TMO])) break; if (_sp > XB_SPIN_CAP) { atomicAdd(&(bar)[XB_TMO], 1u); break; } } } } while (0)
; __device__ __forceinline__ void xcd_barrier(const XcdBarrier& b) {
;     ...
;             asm volatile("s_waitcnt vmcnt(0)" ::: "memory");
;         } else {
;             XB_SPIN(xb_ld(&bar[XB_XGEN(b.x)]) == gen, bar);
;             __builtin_amdgcn_fence(__ATOMIC_ACQUIRE, "agent");
;             asm volatile("s_waitcnt vmcnt(0)" ::: "memory");
;         }
;     }
;     __syncthreads();
.Lgs2_done:
	s_waitcnt vmcnt(0)
	s_branch .Lgs2_pad
	s_nop 0
	s_nop 0
	s_nop 0
	s_nop 0
	s_nop 0
	s_nop 0
	s_nop 0
	s_nop 0
	s_nop 0
	s_nop 0
	s_nop 0
	s_nop 0
	s_nop 0
	s_nop 0
	s_nop 0
	s_nop 0
	s_nop 0
	s_nop 0
	s_nop 0
	s_nop 0
	s_nop 0
	s_nop 0
	s_nop 0
	s_nop 0
	s_nop 0
	s_nop 0
	s_nop 0
	s_nop 0
	s_nop 0
	s_nop 0
	s_nop 0
	s_nop 0
	s_nop 0
	s_nop 0
	s_nop 0
	s_nop 0
	s_nop 0
	s_nop 0
	s_nop 0
	s_nop 0
	s_nop 0
	s_nop 0
	s_nop 0
	s_nop 0
	s_nop 0
	s_nop 0
	s_nop 0
	s_nop 0
	s_nop 0
	s_nop 0
	s_nop 0
	s_nop 0
	s_nop 0
	s_nop 0
	s_nop 0
	s_nop 0
	s_nop 0
	s_nop 0
	s_nop 0
	s_nop 0
	s_nop 0
	s_nop 0
	s_nop 0
	s_nop 0
	s_nop 0
	s_nop 0
	s_nop 0
	s_nop 0
	s_nop 0
	s_nop 0
	s_nop 0
	s_nop 0
	s_nop 0
.Lgs2_pad:
.LBB0_886:
	s_or_b64 exec, exec, s[0:1]
	v_readlane_b32 s0, v253, 56
	v_readlane_b32 s1, v253, 57
	s_andn2_b64 vcc, exec, s[0:1]
	s_waitcnt lgkmcnt(0)
	s_barrier
	s_cbranch_vccnz .LBB0_890
	v_readlane_b32 s0, v254, 61
	v_readlane_b32 s1, v254, 62
	s_lshl_b32 s16, s0, 6
	s_lshl_b32 s0, s0, 8
	s_mov_b32 s1, s17
	s_lshl_b64 s[0:1], s[0:1], 2
	v_readlane_b32 s4, v253, 61
	s_add_u32 s8, s4, s0
	v_readlane_b32 s0, v253, 62
	v_readlane_b32 s44, v253, 38
	s_addc_u32 s9, s0, s1
	s_lshl_b64 s[4:5], s[16:17], 2
	v_mov_b32_e32 v104, v224
	v_mov_b32_e32 v105, v232
	s_mov_b32 s10, s2
	v_readlane_b32 s50, v253, 44
	v_readlane_b32 s51, v253, 45
	v_readlane_b32 s54, v253, 48
	v_readlane_b32 s55, v253, 49
	v_readlane_b32 s19, v253, 1
	v_readlane_b32 s20, v253, 2
	v_readlane_b32 s21, v253, 58
	v_readlane_b32 s22, v253, 59
	v_readlane_b32 s23, v253, 60
	v_readlane_b32 s45, v253, 39
	v_readlane_b32 s46, v253, 40
	v_readlane_b32 s47, v253, 41
	v_readlane_b32 s48, v253, 42
	v_readlane_b32 s49, v253, 43
	v_readlane_b32 s52, v253, 46
	v_readlane_b32 s53, v253, 47
	v_readlane_b32 s56, v253, 50
	v_readlane_b32 s57, v253, 51
	v_readlane_b32 s58, v253, 52
	v_readlane_b32 s59, v253, 53
